# attention A even step: two of the four LDS-DMA piece issues spread into the QK phase (after the 2nd and 4th K-slice MFMA pairs) instead of one 4-issue burst; bases in dedicated SGPRs
# baseline (speedup 1.0000x reference)
; #define ATT_PKN(P, BASE, OUT) do { u32x4 w = {cvtpk(P[BASE + 0], P[BASE + 1]), cvtpk(P[BASE + 2], P[BASE + 3]), cvtpk(P[BASE + 4], P[BASE + 5]), cvtpk(P[BASE + 6], P[BASE + 7])}; OUT = *reinterpret_cast<bf16x8*>(&w); } while (0)
; __device__ __forceinline__ void finishSM(f32x16& p0, f32x16& p1, float alpha, float& l_reg, bf16x8& pa0, bf16x8& pa1, bf16x8& pa2, bf16x8& pa3) {
; #pragma unroll
;   for (int r = 0; r < 16; ++r) p1[r] = __builtin_amdgcn_exp2f(p1[r]);
;   float ps = 0;
; #pragma unroll
;   for (int r = 0; r < 16; ++r) ps += p0[r];
; #pragma unroll
;   for (int r = 0; r < 16; ++r) ps += p1[r];
;   { auto rr = __builtin_amdgcn_permlane32_swap(__float_as_uint(ps), __float_as_uint(ps), false, false);
;     ps = __uint_as_float(rr[0]) + __uint_as_float(rr[1]); }
;   l_reg = l_reg * alpha + ps;
;     ...
;   ATT_PKN(p0, 0, pa0); ATT_PKN(p0, 8, pa1); ATT_PKN(p1, 0, pa2); ATT_PKN(p1, 8, pa3);
;     ...
; }
; __device__ __forceinline__ void qkt(f32x16& p0, f32x16& p1, const bf16* Ks, const bf16x8* qr, int r32, int hi, int mp, const f32x16& negm) {
; #pragma unroll
;   for (int d0 = 0; d0 < 4; ++d0) { int cb = ((mp * 4 + d0) * 16 + hi * 8) * 2;
;     bf16x8 b0 = *reinterpret_cast<const bf16x8*>((const char*)Ks + KSWZ(r32, cb));
;     bf16x8 b1 = *reinterpret_cast<const bf16x8*>((const char*)Ks + KSWZ(32 + r32, cb));
;     if (d0 == 0) { p0 = __builtin_amdgcn_mfma_f32_32x32x16_bf16(b0, qr[0], negm, 0, 0, 0); p1 = __builtin_amdgcn_mfma_f32_32x32x16_bf16(b1, qr[0], negm, 0, 0, 0); }
;     else { p0 = __builtin_amdgcn_mfma_f32_32x32x16_bf16(b0, qr[d0], p0, 0, 0, 0); p1 = __builtin_amdgcn_mfma_f32_32x32x16_bf16(b1, qr[d0], p1, 0, 0, 0); } }
; }
; __device__ __forceinline__ void unit(const bf16* Qb, const bf16* __restrict__ Kh, const bf16* __restrict__ Vh, bf16* Ob, float lam, float post, const float* __restrict__ gsub, char* lds) {
;     ...
;   f32x16 pA0, pA1, pB0, pB1; float alA, alB; bf16x8 pa0, pa1, pa2, pa3; constexpr int NT = 4096 / KVBLK;
;   DMA_TILE(0, 0); DMA_TILE(1, 32768); DMA_TILE(2, 65536);
;   asm volatile("s_waitcnt vmcnt(0)" ::: "memory"); __syncthreads();
;   qkt(pA0, pA1, (const bf16*)(lds + 16384), qr, r32, hi, mp, negm); partialSM<true>(pA0, pA1, m_reg, negm, alA);
;   int sk = 32768, sv = 0, sw = 98304;
.Lprio_skip:
.LBB0_197:
	s_add_i32 s10, s39, 0
	s_add_i32 s13, s21, s56
	s_add_u32 s58, s50, s36
	s_addc_u32 s59, s51, s37
	s_add_u32 s60, s50, 0x4030000
	s_addc_u32 s61, s51, 0
	s_add_u32 s62, s60, 0x80
	s_addc_u32 s63, s61, 0
	v_add_u32_e32 v112, s10, v202
	ds_read_b128 v[236:239], v112 offset:24576
	ds_read_b128 v[112:115], v112 offset:16384
	v_add_u32_e32 v208, s10, v201
	ds_read_b128 v[68:71], v208 offset:24576
	ds_read_b128 v[72:75], v208 offset:16384
	v_add_u32_e32 v208, s10, v199
	v_exp_f32_e32 v210, v96
	v_add_f32_e32 v96, v174, v172
	s_waitcnt lgkmcnt(2)
	v_mfma_f32_32x32x16_bf16 v[128:143], v[112:115], v[158:161], v[80:95]
	v_add_f32_e32 v96, v175, v96
	v_add_f32_e32 v96, v211, v96
	v_mfma_f32_32x32x16_bf16 v[112:127], v[236:239], v[158:161], v[80:95]
	ds_read_b128 v[236:239], v208 offset:24576
	ds_read_b128 v[240:243], v208 offset:16384
	v_add_u32_e32 v208, s10, v183
	v_add_f32_e32 v96, v212, v96
	v_add_f32_e32 v96, v215, v96
	v_add_f32_e32 v96, v216, v96
	v_add_f32_e32 v96, v233, v96
	v_add_f32_e32 v96, v173, v96
	s_waitcnt lgkmcnt(2)
	v_mfma_f32_32x32x16_bf16 v[112:127], v[68:71], v[154:157], v[112:127]
	v_add_f32_e32 v96, v176, v96
	v_add_f32_e32 v96, v177, v96
	v_add_f32_e32 v96, v213, v96
	v_add_f32_e32 v96, v214, v96
	v_exp_f32_e32 v235, v97
	v_add_f32_e32 v96, v217, v96
	v_add_f32_e32 v96, v232, v96
	v_mfma_f32_32x32x16_bf16 v[128:143], v[72:75], v[154:157], v[128:143]
	ds_read_b128 v[68:71], v208 offset:24576
	ds_read_b128 v[72:75], v208 offset:16384
	s_add_i32 m0, s13, 0x4000
	s_nop 0
	global_load_lds_dwordx4 v168, s[58:59]
	v_add_f32_e32 v96, v234, v96
	v_add_f32_e32 v96, v210, v96
	v_add_f32_e32 v96, v235, v96
	v_exp_f32_e32 v244, v106
	v_exp_f32_e32 v245, v107
	s_waitcnt lgkmcnt(2)
	v_mfma_f32_32x32x16_bf16 v[112:127], v[236:239], v[150:153], v[112:127]
	v_exp_f32_e32 v246, v108
	v_exp_f32_e32 v247, v109
	v_exp_f32_e32 v248, v110
	v_exp_f32_e32 v111, v111
	v_cvt_pk_bf16_f32 v97, v175, v211
	v_cvt_pk_bf16_f32 v109, v244, v245
	v_cvt_pk_bf16_f32 v110, v246, v247
	v_mfma_f32_32x32x16_bf16 v[128:143], v[240:243], v[150:153], v[128:143]
	s_waitcnt lgkmcnt(0)
	v_mfma_f32_32x32x16_bf16 v[112:127], v[68:71], v[146:149], v[112:127]
	v_exp_f32_e32 v236, v98
	v_exp_f32_e32 v237, v99
	v_exp_f32_e32 v238, v100
	v_exp_f32_e32 v239, v101
	v_add_f32_e32 v96, v236, v96
	v_add_f32_e32 v96, v237, v96
	v_add_f32_e32 v96, v238, v96
	v_mfma_f32_32x32x16_bf16 v[128:143], v[72:75], v[146:149], v[128:143]
	s_mov_b32 m0, s13
	s_nop 0
	global_load_lds_dwordx4 v188, s[60:61]
	v_exp_f32_e32 v240, v102
	v_exp_f32_e32 v241, v103
	v_exp_f32_e32 v242, v104
	v_exp_f32_e32 v243, v105
	v_add_f32_e32 v96, v239, v96
	v_add_f32_e32 v96, v240, v96
	v_add_f32_e32 v96, v241, v96
	v_add_f32_e32 v96, v242, v96
	v_add_f32_e32 v96, v243, v96
	v_add_f32_e32 v96, v244, v96
	v_add_f32_e32 v96, v245, v96
	v_add_f32_e32 v96, v246, v96
	v_add_f32_e32 v96, v247, v96
	v_add_f32_e32 v96, v248, v96
	v_add_f32_e32 v208, v111, v96
	v_mov_b32_e32 v209, v208
	s_nop 1
	v_permlane32_swap_b32_e32 v208, v209
	v_cvt_pk_bf16_f32 v96, v172, v174
	v_cvt_pk_bf16_f32 v98, v212, v215
	v_cvt_pk_bf16_f32 v99, v216, v233
	v_cvt_pk_bf16_f32 v100, v173, v176
	v_cvt_pk_bf16_f32 v101, v177, v213
	v_cvt_pk_bf16_f32 v102, v214, v217
	v_cvt_pk_bf16_f32 v103, v232, v234
	v_cvt_pk_bf16_f32 v104, v210, v235
	v_cvt_pk_bf16_f32 v105, v236, v237
	v_cvt_pk_bf16_f32 v106, v238, v239
	v_cvt_pk_bf16_f32 v107, v240, v241
	v_cvt_pk_bf16_f32 v108, v242, v243
	v_cvt_pk_bf16_f32 v111, v248, v111
	v_add_u32_e32 v240, s48, v205
	ds_read_b64_tr_b16 v[210:211], v240 offset:0
	ds_read_b64_tr_b16 v[212:213], v240 offset:0x800
	ds_read_b64_tr_b16 v[214:215], v240 offset:0x1000
	ds_read_b64_tr_b16 v[216:217], v240 offset:0x1800
	ds_read_b64_tr_b16 v[232:233], v240 offset:0x2000
	ds_read_b64_tr_b16 v[234:235], v240 offset:0x2800
	ds_read_b64_tr_b16 v[236:237], v240 offset:0x3000
	ds_read_b64_tr_b16 v[238:239], v240 offset:0x3800
	s_add_i32 m0, s13, 0x4400
	s_nop 0
	global_load_lds_dwordx4 v170, s[58:59]
	s_add_i32 m0, s13, 0x400
	s_nop 0
	global_load_lds_dwordx4 v188, s[62:63]
	s_waitcnt lgkmcnt(0)
; #define SBAR() __builtin_amdgcn_sched_barrier(0)
; template <int OFF> __device__ __forceinline__ s16x4 tr_read(int vb) { s16x4 r; asm volatile("ds_read_b64_tr_b16 %0, %1 offset:%2" : "=&v"(r) : "v"(vb), "i"(OFF) : "memory"); return r; }
; template <bool FIRST> __device__ __forceinline__ void partialSM(f32x16& p0, f32x16& p1, float& m_reg, f32x16& negm, float& alpha) {
;   float pmax = p0[0];
; #pragma unroll
;   for (int r = 1; r < 16; ++r) pmax = fmaxf(pmax, p0[r]);
; #pragma unroll
;   for (int r = 0; r < 16; ++r) pmax = fmaxf(pmax, p1[r]);
;   { auto rr = __builtin_amdgcn_permlane32_swap(__float_as_uint(pmax), __float_as_uint(pmax), false, false);
;     pmax = fmaxf(__uint_as_float(rr[0]), __uint_as_float(rr[1])); }
;   alpha = 1.f;
;   if (FIRST || __builtin_expect(__any(pmax > THR), 0)) { const float dl = FIRST ? pmax : fmaxf(pmax, 0.f); m_reg += dl; if (!FIRST) alpha = __builtin_amdgcn_exp2f(-dl);
; template <int D0> __device__ __forceinline__ void pv_one(f32x16& od, int vb, bf16x8 pa0, bf16x8 pa1, bf16x8 pa2, bf16x8 pa3) {
;   const s16x4 l0 = tr_read<v_rd_off(D0, 0, 0)>(vb), h0 = tr_read<v_rd_off(D0, 0, 1)>(vb), l1 = tr_read<v_rd_off(D0, 1, 0)>(vb), h1 = tr_read<v_rd_off(D0, 1, 1)>(vb);
;   const s16x4 l2 = tr_read<v_rd_off(D0, 2, 0)>(vb), h2 = tr_read<v_rd_off(D0, 2, 1)>(vb), l3 = tr_read<v_rd_off(D0, 3, 0)>(vb), h3 = tr_read<v_rd_off(D0, 3, 1)>(vb);
;   asm volatile("s_waitcnt lgkmcnt(0)" ::: "memory"); SBAR();
;   od = __builtin_amdgcn_mfma_f32_32x32x16_bf16(pa0, ATT_PK(l0, h0), od, 0, 0, 0);
;   od = __builtin_amdgcn_mfma_f32_32x32x16_bf16(pa1, ATT_PK(l1, h1), od, 0, 0, 0);
;   od = __builtin_amdgcn_mfma_f32_32x32x16_bf16(pa2, ATT_PK(l2, h2), od, 0, 0, 0);
;   od = __builtin_amdgcn_mfma_f32_32x32x16_bf16(pa3, ATT_PK(l3, h3), od, 0, 0, 0);
; }
; __device__ __forceinline__ void pv_d0(f32x16* o, int vb, bf16x8 pa0, bf16x8 pa1, bf16x8 pa2, bf16x8 pa3) {
;   pv_one<0>(o[0], vb, pa0, pa1, pa2, pa3); pv_one<1>(o[1], vb, pa0, pa1, pa2, pa3); pv_one<2>(o[2], vb, pa0, pa1, pa2, pa3); pv_one<3>(o[3], vb, pa0, pa1, pa2, pa3);
	s_nop 0
	v_mfma_f32_32x32x16_bf16 v[0:15], v[96:99], v[210:213], v[0:15]
	ds_read_b64_tr_b16 v[210:211], v240 offset:0x200
	ds_read_b64_tr_b16 v[212:213], v240 offset:0xa00
	v_mfma_f32_32x32x16_bf16 v[0:15], v[100:103], v[214:217], v[0:15]
	ds_read_b64_tr_b16 v[214:215], v240 offset:0x1200
	ds_read_b64_tr_b16 v[216:217], v240 offset:0x1a00
	v_mfma_f32_32x32x16_bf16 v[0:15], v[104:107], v[232:235], v[0:15]
	ds_read_b64_tr_b16 v[232:233], v240 offset:0x2200
	ds_read_b64_tr_b16 v[234:235], v240 offset:0x2a00
	v_mfma_f32_32x32x16_bf16 v[0:15], v[108:111], v[236:239], v[0:15]
	ds_read_b64_tr_b16 v[236:237], v240 offset:0x3200
	ds_read_b64_tr_b16 v[238:239], v240 offset:0x3a00
	s_waitcnt lgkmcnt(0)
	v_mfma_f32_32x32x16_bf16 v[48:63], v[96:99], v[210:213], v[48:63]
	ds_read_b64_tr_b16 v[210:211], v240 offset:0x400
	ds_read_b64_tr_b16 v[212:213], v240 offset:0xc00
	v_mfma_f32_32x32x16_bf16 v[48:63], v[100:103], v[214:217], v[48:63]
	ds_read_b64_tr_b16 v[214:215], v240 offset:0x1400
	ds_read_b64_tr_b16 v[216:217], v240 offset:0x1c00
	v_mfma_f32_32x32x16_bf16 v[48:63], v[104:107], v[232:235], v[48:63]
	ds_read_b64_tr_b16 v[232:233], v240 offset:0x2400
	ds_read_b64_tr_b16 v[234:235], v240 offset:0x2c00
	v_mfma_f32_32x32x16_bf16 v[48:63], v[108:111], v[236:239], v[48:63]
	ds_read_b64_tr_b16 v[236:237], v240 offset:0x3400
	ds_read_b64_tr_b16 v[238:239], v240 offset:0x3c00
	s_waitcnt lgkmcnt(0)
	v_mfma_f32_32x32x16_bf16 v[32:47], v[96:99], v[210:213], v[32:47]
	ds_read_b64_tr_b16 v[210:211], v240 offset:0x600
	ds_read_b64_tr_b16 v[212:213], v240 offset:0xe00
	v_mfma_f32_32x32x16_bf16 v[32:47], v[100:103], v[214:217], v[32:47]
	ds_read_b64_tr_b16 v[214:215], v240 offset:0x1600
	ds_read_b64_tr_b16 v[216:217], v240 offset:0x1e00
	v_mfma_f32_32x32x16_bf16 v[32:47], v[104:107], v[232:235], v[32:47]
	ds_read_b64_tr_b16 v[232:233], v240 offset:0x2600
	ds_read_b64_tr_b16 v[234:235], v240 offset:0x2e00
	v_mfma_f32_32x32x16_bf16 v[32:47], v[108:111], v[236:239], v[32:47]
	ds_read_b64_tr_b16 v[236:237], v240 offset:0x3600
	ds_read_b64_tr_b16 v[238:239], v240 offset:0x3e00
	s_waitcnt lgkmcnt(0)
	v_mfma_f32_32x32x16_bf16 v[16:31], v[96:99], v[210:213], v[16:31]
	v_max_f32_e32 v96, v129, v129
	v_max_f32_e32 v97, v128, v128
	v_max_f32_e32 v96, v97, v96
	v_max3_f32 v96, v96, v130, v131
	v_max3_f32 v96, v96, v132, v133
	v_max3_f32 v96, v96, v134, v135
	v_max3_f32 v96, v96, v136, v137
	v_mfma_f32_32x32x16_bf16 v[16:31], v[100:103], v[214:217], v[16:31]
	v_max3_f32 v96, v96, v138, v139
	v_max3_f32 v96, v96, v140, v141
	v_max3_f32 v96, v96, v142, v143
	v_max3_f32 v96, v96, v112, v113
	v_max3_f32 v96, v96, v114, v115
	v_max3_f32 v96, v96, v116, v117
	v_max3_f32 v96, v96, v118, v119
	v_mfma_f32_32x32x16_bf16 v[16:31], v[104:107], v[232:235], v[16:31]
	v_max3_f32 v96, v96, v120, v121
	v_max3_f32 v96, v96, v122, v123
	v_max3_f32 v96, v96, v124, v125
	v_max3_f32 v96, v96, v126, v127
	v_mov_b32_e32 v97, v96
	s_nop 1
	v_permlane32_swap_b32_e32 v96, v97
	v_mfma_f32_32x32x16_bf16 v[16:31], v[108:111], v[236:239], v[16:31]
	v_max_f32_e32 v96, v96, v97
	v_cmp_lt_f32_e32 vcc, s19, v96
	s_cbranch_vccnz .LBB0_215
	v_mov_b32_e32 v210, 1.0
	s_branch .LBB0_202
